# v181 with the P6 h1b residual loads issued without the nt hint
# speedup vs baseline: 1.0035x; 1.0035x over previous
; __device__ __forceinline__ void unpack8(const u32x4 w, float (&f)[8]) { f[0] = bflo(w.x); f[1] = bfhi(w.x); f[2] = bflo(w.y); f[3] = bfhi(w.y); f[4] = bflo(w.z); f[5] = bfhi(w.z); f[6] = bflo(w.w); f[7] = bfhi(w.w); }
;     __device__ __forceinline__ void operator()(const f32x4 (&acc)[2][2][4][2], const Unit& u, int wr, int wc, int fr, int fq) const {
;         const int row0 = u.pm * BM + wr * 64 + fr, col0 = u.pn * BM + wc * 32 + 8 * fq;
; #pragma unroll
;         for (int ai = 0; ai < 2; ++ai)
; #pragma unroll
;             for (int m = 0; m < 4; ++m) { const size_t idx = (size_t)(row0 + ai * HALF + m * 16) * 1024 + col0;
; #pragma unroll
;                 for (int bj = 0; bj < 2; ++bj) { float h[8]; unpack8(__builtin_nontemporal_load((const u32x4*)(h1b + idx + bj * HALF)), h);
;                     const f32x4 a0 = acc[ai][bj][m][0], a1 = acc[ai][bj][m][1];
;                     __builtin_nontemporal_store(((f32x4){h[0] + a0[0], h[1] + a0[1], h[2] + a0[2], h[3] + a0[3]}), (f32x4*)(out + idx + bj * HALF));
;                     __builtin_nontemporal_store(((f32x4){h[4] + a1[0], h[5] + a1[1], h[6] + a1[2], h[7] + a1[3]}), (f32x4*)(out + idx + bj * HALF + 4)); } }
.LBB0_816:
	v_lshl_add_u32 v232, s28, 8, v150
	v_lshl_or_b32 v233, s47, 8, v152
	v_lshl_add_u32 v232, v232, 10, v233
	v_lshlrev_b32_e32 v232, 1, v232
	global_load_dwordx4 v[156:159], v232, s[8:9]
	global_load_dwordx4 v[160:163], v232, s[8:9] offset:256
	v_add_u32_e32 v232, 0x8000, v232
	global_load_dwordx4 v[164:167], v232, s[8:9]
	global_load_dwordx4 v[168:171], v232, s[8:9] offset:256
	v_add_u32_e32 v232, 0x8000, v232
	global_load_dwordx4 v[172:175], v232, s[8:9]
	global_load_dwordx4 v[176:179], v232, s[8:9] offset:256
	v_add_u32_e32 v232, 0x8000, v232
	global_load_dwordx4 v[180:183], v232, s[8:9]
	global_load_dwordx4 v[184:187], v232, s[8:9] offset:256
	v_add_u32_e32 v232, 0x28000, v232
	global_load_dwordx4 v[188:191], v232, s[8:9]
	global_load_dwordx4 v[192:195], v232, s[8:9] offset:256
	v_add_u32_e32 v232, 0x8000, v232
	global_load_dwordx4 v[196:199], v232, s[8:9]
	global_load_dwordx4 v[200:203], v232, s[8:9] offset:256
	v_add_u32_e32 v232, 0x8000, v232
	global_load_dwordx4 v[204:207], v232, s[8:9]
	global_load_dwordx4 v[208:211], v232, s[8:9] offset:256
	v_add_u32_e32 v232, 0x8000, v232
	global_load_dwordx4 v[212:215], v232, s[8:9]
	global_load_dwordx4 v[216:219], v232, s[8:9] offset:256
	v_mbcnt_lo_u32_b32 v224, -1, 0
	v_mbcnt_hi_u32_b32 v224, -1, v224
	v_bfe_u32 v225, v150, 6, 1
	v_bfe_u32 v226, v152, 5, 2
	v_lshl_or_b32 v225, v225, 2, v226
	v_lshlrev_b32_e32 v225, 10, v225
	v_add_u32_e32 v225, 0x20000, v225
	v_and_b32_e32 v226, 7, v150
	v_bfe_u32 v227, v152, 3, 2
	v_lshlrev_b32_e32 v227, 1, v227
	v_xor_b32_e32 v228, v227, v226
	v_lshlrev_b32_e32 v228, 4, v228
	v_lshl_add_u32 v234, v226, 7, v228
	v_add_u32_e32 v234, v234, v225
	v_or_b32_e32 v227, 1, v227
	v_xor_b32_e32 v228, v227, v226
	v_lshlrev_b32_e32 v228, 4, v228
	v_lshl_add_u32 v235, v226, 7, v228
	v_add_u32_e32 v235, v235, v225
	v_lshrrev_b32_e32 v226, 3, v224
	v_and_b32_e32 v227, 7, v224
	v_xor_b32_e32 v228, v227, v226
	v_lshlrev_b32_e32 v228, 4, v228
	v_lshl_add_u32 v236, v226, 7, v228
	v_add_u32_e32 v236, v236, v225
	v_and_b32_e32 v228, 0xfffffff0, v150
	v_add_u32_e32 v228, v228, v226
	v_lshl_add_u32 v228, s28, 8, v228
	v_and_b32_e32 v229, 0xffffffe7, v152
	v_lshl_or_b32 v229, s47, 8, v229
	v_lshl_add_u32 v229, v227, 2, v229
	v_lshl_add_u32 v228, v228, 10, v229
	v_lshlrev_b32_e32 v233, 2, v228
	v_add_u32_e32 v237, 0x8000, v233
	s_mov_b32 s98, 0x00ff00ff
	s_mov_b32 s99, 0x00ff00ff
	s_mov_b32 s100, 0xff00ff00
	s_mov_b32 s101, 0xff00ff00
	s_waitcnt vmcnt(14)
	v_lshlrev_b32_e32 v224, 16, v156
	v_and_b32_e32 v225, 0xffff0000, v156
	v_lshlrev_b32_e32 v226, 16, v157
	v_and_b32_e32 v227, 0xffff0000, v157
	v_lshlrev_b32_e32 v228, 16, v158
	v_and_b32_e32 v229, 0xffff0000, v158
	v_lshlrev_b32_e32 v230, 16, v159
	v_and_b32_e32 v231, 0xffff0000, v159
	v_pk_add_f32 v[124:125], v[124:125], v[224:225]
	v_pk_add_f32 v[126:127], v[126:127], v[226:227]
	v_pk_add_f32 v[120:121], v[120:121], v[228:229]
	v_pk_add_f32 v[122:123], v[122:123], v[230:231]
	s_mov_b64 exec, s[98:99]
	ds_write_b128 v234, v[124:127]
	ds_write_b128 v235, v[120:123]
	s_mov_b64 exec, -1
	ds_read_b128 v[238:241], v236
	s_mov_b64 exec, s[100:101]
	ds_write_b128 v234, v[124:127]
	ds_write_b128 v235, v[120:123]
	s_mov_b64 exec, -1
	ds_read_b128 v[242:245], v236
	s_waitcnt lgkmcnt(3)
	global_store_dwordx4 v233, v[238:241], s[50:51] nt
	s_waitcnt lgkmcnt(0)
	global_store_dwordx4 v237, v[242:245], s[50:51] nt
	v_lshlrev_b32_e32 v224, 16, v160
	v_and_b32_e32 v225, 0xffff0000, v160
	v_lshlrev_b32_e32 v226, 16, v161
	v_and_b32_e32 v227, 0xffff0000, v161
	v_lshlrev_b32_e32 v228, 16, v162
	v_and_b32_e32 v229, 0xffff0000, v162
	v_lshlrev_b32_e32 v230, 16, v163
	v_and_b32_e32 v231, 0xffff0000, v163
	v_pk_add_f32 v[116:117], v[116:117], v[224:225]
	v_pk_add_f32 v[118:119], v[118:119], v[226:227]
	v_pk_add_f32 v[112:113], v[112:113], v[228:229]
	v_pk_add_f32 v[114:115], v[114:115], v[230:231]
	s_mov_b64 exec, s[98:99]
	ds_write_b128 v234, v[116:119]
	ds_write_b128 v235, v[112:115]
	s_mov_b64 exec, -1
	ds_read_b128 v[238:241], v236
	s_mov_b64 exec, s[100:101]
	ds_write_b128 v234, v[116:119]
	ds_write_b128 v235, v[112:115]
	s_mov_b64 exec, -1
	ds_read_b128 v[242:245], v236
	s_waitcnt lgkmcnt(3)
	global_store_dwordx4 v233, v[238:241], s[50:51] offset:512 nt
	s_waitcnt lgkmcnt(0)
	global_store_dwordx4 v237, v[242:245], s[50:51] offset:512 nt
	v_add_u32_e32 v233, 0x10000, v233
	v_add_u32_e32 v237, 0x10000, v237
	s_waitcnt vmcnt(16)
	v_lshlrev_b32_e32 v224, 16, v164
	v_and_b32_e32 v225, 0xffff0000, v164
	v_lshlrev_b32_e32 v226, 16, v165
	v_and_b32_e32 v227, 0xffff0000, v165
	v_lshlrev_b32_e32 v228, 16, v166
	v_and_b32_e32 v229, 0xffff0000, v166
	v_lshlrev_b32_e32 v230, 16, v167
	v_and_b32_e32 v231, 0xffff0000, v167
	v_pk_add_f32 v[108:109], v[108:109], v[224:225]
	v_pk_add_f32 v[110:111], v[110:111], v[226:227]
	v_pk_add_f32 v[104:105], v[104:105], v[228:229]
	v_pk_add_f32 v[106:107], v[106:107], v[230:231]
	s_mov_b64 exec, s[98:99]
	ds_write_b128 v234, v[108:111]
	ds_write_b128 v235, v[104:107]
	s_mov_b64 exec, -1
	ds_read_b128 v[238:241], v236
	s_mov_b64 exec, s[100:101]
	ds_write_b128 v234, v[108:111]
	ds_write_b128 v235, v[104:107]
	s_mov_b64 exec, -1
	ds_read_b128 v[242:245], v236
	s_waitcnt lgkmcnt(3)
	global_store_dwordx4 v233, v[238:241], s[50:51] nt
	s_waitcnt lgkmcnt(0)
; __device__ __forceinline__ void unpack8(const u32x4 w, float (&f)[8]) { f[0] = bflo(w.x); f[1] = bfhi(w.x); f[2] = bflo(w.y); f[3] = bfhi(w.y); f[4] = bflo(w.z); f[5] = bfhi(w.z); f[6] = bflo(w.w); f[7] = bfhi(w.w); }
;     __device__ __forceinline__ void operator()(const f32x4 (&acc)[2][2][4][2], const Unit& u, int wr, int wc, int fr, int fq) const {
;         const int row0 = u.pm * BM + wr * 64 + fr, col0 = u.pn * BM + wc * 32 + 8 * fq;
; #pragma unroll
;         for (int ai = 0; ai < 2; ++ai)
; #pragma unroll
;             for (int m = 0; m < 4; ++m) { const size_t idx = (size_t)(row0 + ai * HALF + m * 16) * 1024 + col0;
; #pragma unroll
;                 for (int bj = 0; bj < 2; ++bj) { float h[8]; unpack8(__builtin_nontemporal_load((const u32x4*)(h1b + idx + bj * HALF)), h);
;                     const f32x4 a0 = acc[ai][bj][m][0], a1 = acc[ai][bj][m][1];
;                     __builtin_nontemporal_store(((f32x4){h[0] + a0[0], h[1] + a0[1], h[2] + a0[2], h[3] + a0[3]}), (f32x4*)(out + idx + bj * HALF));
;                     __builtin_nontemporal_store(((f32x4){h[4] + a1[0], h[5] + a1[1], h[6] + a1[2], h[7] + a1[3]}), (f32x4*)(out + idx + bj * HALF + 4)); } }
	global_store_dwordx4 v237, v[242:245], s[50:51] nt
	v_lshlrev_b32_e32 v224, 16, v168
	v_and_b32_e32 v225, 0xffff0000, v168
	v_lshlrev_b32_e32 v226, 16, v169
	v_and_b32_e32 v227, 0xffff0000, v169
	v_lshlrev_b32_e32 v228, 16, v170
	v_and_b32_e32 v229, 0xffff0000, v170
	v_lshlrev_b32_e32 v230, 16, v171
	v_and_b32_e32 v231, 0xffff0000, v171
	v_pk_add_f32 v[100:101], v[100:101], v[224:225]
	v_pk_add_f32 v[102:103], v[102:103], v[226:227]
	v_pk_add_f32 v[96:97], v[96:97], v[228:229]
	v_pk_add_f32 v[98:99], v[98:99], v[230:231]
	s_mov_b64 exec, s[98:99]
	ds_write_b128 v234, v[100:103]
	ds_write_b128 v235, v[96:99]
	s_mov_b64 exec, -1
	ds_read_b128 v[238:241], v236
	s_mov_b64 exec, s[100:101]
	ds_write_b128 v234, v[100:103]
	ds_write_b128 v235, v[96:99]
	s_mov_b64 exec, -1
	ds_read_b128 v[242:245], v236
	s_waitcnt lgkmcnt(3)
	global_store_dwordx4 v233, v[238:241], s[50:51] offset:512 nt
	s_waitcnt lgkmcnt(0)
	global_store_dwordx4 v237, v[242:245], s[50:51] offset:512 nt
	v_add_u32_e32 v233, 0x10000, v233
	v_add_u32_e32 v237, 0x10000, v237
	s_waitcnt vmcnt(18)
	v_lshlrev_b32_e32 v224, 16, v172
	v_and_b32_e32 v225, 0xffff0000, v172
	v_lshlrev_b32_e32 v226, 16, v173
	v_and_b32_e32 v227, 0xffff0000, v173
	v_lshlrev_b32_e32 v228, 16, v174
	v_and_b32_e32 v229, 0xffff0000, v174
	v_lshlrev_b32_e32 v230, 16, v175
	v_and_b32_e32 v231, 0xffff0000, v175
	v_pk_add_f32 v[92:93], v[92:93], v[224:225]
	v_pk_add_f32 v[94:95], v[94:95], v[226:227]
	v_pk_add_f32 v[88:89], v[88:89], v[228:229]
	v_pk_add_f32 v[90:91], v[90:91], v[230:231]
	s_mov_b64 exec, s[98:99]
	ds_write_b128 v234, v[92:95]
	ds_write_b128 v235, v[88:91]
	s_mov_b64 exec, -1
	ds_read_b128 v[238:241], v236
	s_mov_b64 exec, s[100:101]
	ds_write_b128 v234, v[92:95]
	ds_write_b128 v235, v[88:91]
	s_mov_b64 exec, -1
	ds_read_b128 v[242:245], v236
	s_waitcnt lgkmcnt(3)
	global_store_dwordx4 v233, v[238:241], s[50:51] nt
	s_waitcnt lgkmcnt(0)
	global_store_dwordx4 v237, v[242:245], s[50:51] nt
	v_lshlrev_b32_e32 v224, 16, v176
	v_and_b32_e32 v225, 0xffff0000, v176
	v_lshlrev_b32_e32 v226, 16, v177
	v_and_b32_e32 v227, 0xffff0000, v177
	v_lshlrev_b32_e32 v228, 16, v178
	v_and_b32_e32 v229, 0xffff0000, v178
	v_lshlrev_b32_e32 v230, 16, v179
	v_and_b32_e32 v231, 0xffff0000, v179
	v_pk_add_f32 v[84:85], v[84:85], v[224:225]
	v_pk_add_f32 v[86:87], v[86:87], v[226:227]
	v_pk_add_f32 v[80:81], v[80:81], v[228:229]
	v_pk_add_f32 v[82:83], v[82:83], v[230:231]
	s_mov_b64 exec, s[98:99]
	ds_write_b128 v234, v[84:87]
	ds_write_b128 v235, v[80:83]
	s_mov_b64 exec, -1
	ds_read_b128 v[238:241], v236
	s_mov_b64 exec, s[100:101]
	ds_write_b128 v234, v[84:87]
	ds_write_b128 v235, v[80:83]
	s_mov_b64 exec, -1
	ds_read_b128 v[242:245], v236
	s_waitcnt lgkmcnt(3)
	global_store_dwordx4 v233, v[238:241], s[50:51] offset:512 nt
	s_waitcnt lgkmcnt(0)
	global_store_dwordx4 v237, v[242:245], s[50:51] offset:512 nt
	v_add_u32_e32 v233, 0x10000, v233
	v_add_u32_e32 v237, 0x10000, v237
	s_waitcnt vmcnt(20)
	v_lshlrev_b32_e32 v224, 16, v180
	v_and_b32_e32 v225, 0xffff0000, v180
	v_lshlrev_b32_e32 v226, 16, v181
	v_and_b32_e32 v227, 0xffff0000, v181
	v_lshlrev_b32_e32 v228, 16, v182
	v_and_b32_e32 v229, 0xffff0000, v182
	v_lshlrev_b32_e32 v230, 16, v183
	v_and_b32_e32 v231, 0xffff0000, v183
	v_pk_add_f32 v[76:77], v[76:77], v[224:225]
	v_pk_add_f32 v[78:79], v[78:79], v[226:227]
	v_pk_add_f32 v[72:73], v[72:73], v[228:229]
	v_pk_add_f32 v[74:75], v[74:75], v[230:231]
	s_mov_b64 exec, s[98:99]
	ds_write_b128 v234, v[76:79]
	ds_write_b128 v235, v[72:75]
	s_mov_b64 exec, -1
	ds_read_b128 v[238:241], v236
	s_mov_b64 exec, s[100:101]
	ds_write_b128 v234, v[76:79]
	ds_write_b128 v235, v[72:75]
	s_mov_b64 exec, -1
	ds_read_b128 v[242:245], v236
	s_waitcnt lgkmcnt(3)
	global_store_dwordx4 v233, v[238:241], s[50:51] nt
	s_waitcnt lgkmcnt(0)
	global_store_dwordx4 v237, v[242:245], s[50:51] nt
	v_lshlrev_b32_e32 v224, 16, v184
	v_and_b32_e32 v225, 0xffff0000, v184
	v_lshlrev_b32_e32 v226, 16, v185
	v_and_b32_e32 v227, 0xffff0000, v185
	v_lshlrev_b32_e32 v228, 16, v186
	v_and_b32_e32 v229, 0xffff0000, v186
	v_lshlrev_b32_e32 v230, 16, v187
	v_and_b32_e32 v231, 0xffff0000, v187
	v_pk_add_f32 v[68:69], v[68:69], v[224:225]
	v_pk_add_f32 v[70:71], v[70:71], v[226:227]
	v_pk_add_f32 v[64:65], v[64:65], v[228:229]
	v_pk_add_f32 v[66:67], v[66:67], v[230:231]
	s_mov_b64 exec, s[98:99]
	ds_write_b128 v234, v[68:71]
	ds_write_b128 v235, v[64:67]
	s_mov_b64 exec, -1
	ds_read_b128 v[238:241], v236
	s_mov_b64 exec, s[100:101]
	ds_write_b128 v234, v[68:71]
	ds_write_b128 v235, v[64:67]
	s_mov_b64 exec, -1
	ds_read_b128 v[242:245], v236
	s_waitcnt lgkmcnt(3)
	global_store_dwordx4 v233, v[238:241], s[50:51] offset:512 nt
	s_waitcnt lgkmcnt(0)
	global_store_dwordx4 v237, v[242:245], s[50:51] offset:512 nt
	v_add_u32_e32 v233, 0x50000, v233
	v_add_u32_e32 v237, 0x50000, v237
	s_waitcnt vmcnt(22)
	v_lshlrev_b32_e32 v224, 16, v188
	v_and_b32_e32 v225, 0xffff0000, v188
	v_lshlrev_b32_e32 v226, 16, v189
	v_and_b32_e32 v227, 0xffff0000, v189
	v_lshlrev_b32_e32 v228, 16, v190
	v_and_b32_e32 v229, 0xffff0000, v190
	v_lshlrev_b32_e32 v230, 16, v191
	v_and_b32_e32 v231, 0xffff0000, v191
	v_pk_add_f32 v[60:61], v[60:61], v[224:225]
	v_pk_add_f32 v[62:63], v[62:63], v[226:227]
	v_pk_add_f32 v[56:57], v[56:57], v[228:229]
	v_pk_add_f32 v[58:59], v[58:59], v[230:231]
	s_mov_b64 exec, s[98:99]
	ds_write_b128 v234, v[60:63]
	ds_write_b128 v235, v[56:59]
	s_mov_b64 exec, -1
	ds_read_b128 v[238:241], v236
	s_mov_b64 exec, s[100:101]
	ds_write_b128 v234, v[60:63]
	ds_write_b128 v235, v[56:59]
	s_mov_b64 exec, -1
	ds_read_b128 v[242:245], v236
	s_waitcnt lgkmcnt(3)
; __device__ __forceinline__ void unpack8(const u32x4 w, float (&f)[8]) { f[0] = bflo(w.x); f[1] = bfhi(w.x); f[2] = bflo(w.y); f[3] = bfhi(w.y); f[4] = bflo(w.z); f[5] = bfhi(w.z); f[6] = bflo(w.w); f[7] = bfhi(w.w); }
;     __device__ __forceinline__ void operator()(const f32x4 (&acc)[2][2][4][2], const Unit& u, int wr, int wc, int fr, int fq) const {
;         const int row0 = u.pm * BM + wr * 64 + fr, col0 = u.pn * BM + wc * 32 + 8 * fq;
; #pragma unroll
;         for (int ai = 0; ai < 2; ++ai)
; #pragma unroll
;             for (int m = 0; m < 4; ++m) { const size_t idx = (size_t)(row0 + ai * HALF + m * 16) * 1024 + col0;
; #pragma unroll
;                 for (int bj = 0; bj < 2; ++bj) { float h[8]; unpack8(__builtin_nontemporal_load((const u32x4*)(h1b + idx + bj * HALF)), h);
;                     const f32x4 a0 = acc[ai][bj][m][0], a1 = acc[ai][bj][m][1];
;                     __builtin_nontemporal_store(((f32x4){h[0] + a0[0], h[1] + a0[1], h[2] + a0[2], h[3] + a0[3]}), (f32x4*)(out + idx + bj * HALF));
;                     __builtin_nontemporal_store(((f32x4){h[4] + a1[0], h[5] + a1[1], h[6] + a1[2], h[7] + a1[3]}), (f32x4*)(out + idx + bj * HALF + 4)); } }
	global_store_dwordx4 v233, v[238:241], s[50:51] nt
	s_waitcnt lgkmcnt(0)
	global_store_dwordx4 v237, v[242:245], s[50:51] nt
	v_lshlrev_b32_e32 v224, 16, v192
	v_and_b32_e32 v225, 0xffff0000, v192
	v_lshlrev_b32_e32 v226, 16, v193
	v_and_b32_e32 v227, 0xffff0000, v193
	v_lshlrev_b32_e32 v228, 16, v194
	v_and_b32_e32 v229, 0xffff0000, v194
	v_lshlrev_b32_e32 v230, 16, v195
	v_and_b32_e32 v231, 0xffff0000, v195
	v_pk_add_f32 v[52:53], v[52:53], v[224:225]
	v_pk_add_f32 v[54:55], v[54:55], v[226:227]
	v_pk_add_f32 v[48:49], v[48:49], v[228:229]
	v_pk_add_f32 v[50:51], v[50:51], v[230:231]
	s_mov_b64 exec, s[98:99]
	ds_write_b128 v234, v[52:55]
	ds_write_b128 v235, v[48:51]
	s_mov_b64 exec, -1
	ds_read_b128 v[238:241], v236
	s_mov_b64 exec, s[100:101]
	ds_write_b128 v234, v[52:55]
	ds_write_b128 v235, v[48:51]
	s_mov_b64 exec, -1
	ds_read_b128 v[242:245], v236
	s_waitcnt lgkmcnt(3)
	global_store_dwordx4 v233, v[238:241], s[50:51] offset:512 nt
	s_waitcnt lgkmcnt(0)
	global_store_dwordx4 v237, v[242:245], s[50:51] offset:512 nt
	v_add_u32_e32 v233, 0x10000, v233
	v_add_u32_e32 v237, 0x10000, v237
	s_waitcnt vmcnt(24)
	v_lshlrev_b32_e32 v224, 16, v196
	v_and_b32_e32 v225, 0xffff0000, v196
	v_lshlrev_b32_e32 v226, 16, v197
	v_and_b32_e32 v227, 0xffff0000, v197
	v_lshlrev_b32_e32 v228, 16, v198
	v_and_b32_e32 v229, 0xffff0000, v198
	v_lshlrev_b32_e32 v230, 16, v199
	v_and_b32_e32 v231, 0xffff0000, v199
	v_pk_add_f32 v[44:45], v[44:45], v[224:225]
	v_pk_add_f32 v[46:47], v[46:47], v[226:227]
	v_pk_add_f32 v[40:41], v[40:41], v[228:229]
	v_pk_add_f32 v[42:43], v[42:43], v[230:231]
	s_mov_b64 exec, s[98:99]
	ds_write_b128 v234, v[44:47]
	ds_write_b128 v235, v[40:43]
	s_mov_b64 exec, -1
	ds_read_b128 v[238:241], v236
	s_mov_b64 exec, s[100:101]
	ds_write_b128 v234, v[44:47]
	ds_write_b128 v235, v[40:43]
	s_mov_b64 exec, -1
	ds_read_b128 v[242:245], v236
	s_waitcnt lgkmcnt(3)
	global_store_dwordx4 v233, v[238:241], s[50:51] nt
	s_waitcnt lgkmcnt(0)
	global_store_dwordx4 v237, v[242:245], s[50:51] nt
	v_lshlrev_b32_e32 v224, 16, v200
	v_and_b32_e32 v225, 0xffff0000, v200
	v_lshlrev_b32_e32 v226, 16, v201
	v_and_b32_e32 v227, 0xffff0000, v201
	v_lshlrev_b32_e32 v228, 16, v202
	v_and_b32_e32 v229, 0xffff0000, v202
	v_lshlrev_b32_e32 v230, 16, v203
	v_and_b32_e32 v231, 0xffff0000, v203
	v_pk_add_f32 v[36:37], v[36:37], v[224:225]
	v_pk_add_f32 v[38:39], v[38:39], v[226:227]
	v_pk_add_f32 v[32:33], v[32:33], v[228:229]
	v_pk_add_f32 v[34:35], v[34:35], v[230:231]
	s_mov_b64 exec, s[98:99]
	ds_write_b128 v234, v[36:39]
	ds_write_b128 v235, v[32:35]
	s_mov_b64 exec, -1
	ds_read_b128 v[238:241], v236
	s_mov_b64 exec, s[100:101]
	ds_write_b128 v234, v[36:39]
	ds_write_b128 v235, v[32:35]
	s_mov_b64 exec, -1
	ds_read_b128 v[242:245], v236
	s_waitcnt lgkmcnt(3)
	global_store_dwordx4 v233, v[238:241], s[50:51] offset:512 nt
	s_waitcnt lgkmcnt(0)
	global_store_dwordx4 v237, v[242:245], s[50:51] offset:512 nt
	v_add_u32_e32 v233, 0x10000, v233
	v_add_u32_e32 v237, 0x10000, v237
	s_waitcnt vmcnt(26)
	v_lshlrev_b32_e32 v224, 16, v204
	v_and_b32_e32 v225, 0xffff0000, v204
	v_lshlrev_b32_e32 v226, 16, v205
	v_and_b32_e32 v227, 0xffff0000, v205
	v_lshlrev_b32_e32 v228, 16, v206
	v_and_b32_e32 v229, 0xffff0000, v206
	v_lshlrev_b32_e32 v230, 16, v207
	v_and_b32_e32 v231, 0xffff0000, v207
	v_pk_add_f32 v[28:29], v[28:29], v[224:225]
	v_pk_add_f32 v[30:31], v[30:31], v[226:227]
	v_pk_add_f32 v[24:25], v[24:25], v[228:229]
	v_pk_add_f32 v[26:27], v[26:27], v[230:231]
	s_mov_b64 exec, s[98:99]
	ds_write_b128 v234, v[28:31]
	ds_write_b128 v235, v[24:27]
	s_mov_b64 exec, -1
	ds_read_b128 v[238:241], v236
	s_mov_b64 exec, s[100:101]
	ds_write_b128 v234, v[28:31]
	ds_write_b128 v235, v[24:27]
	s_mov_b64 exec, -1
	ds_read_b128 v[242:245], v236
	s_waitcnt lgkmcnt(3)
	global_store_dwordx4 v233, v[238:241], s[50:51] nt
	s_waitcnt lgkmcnt(0)
	global_store_dwordx4 v237, v[242:245], s[50:51] nt
	v_lshlrev_b32_e32 v224, 16, v208
	v_and_b32_e32 v225, 0xffff0000, v208
	v_lshlrev_b32_e32 v226, 16, v209
	v_and_b32_e32 v227, 0xffff0000, v209
	v_lshlrev_b32_e32 v228, 16, v210
	v_and_b32_e32 v229, 0xffff0000, v210
	v_lshlrev_b32_e32 v230, 16, v211
	v_and_b32_e32 v231, 0xffff0000, v211
	v_pk_add_f32 v[20:21], v[20:21], v[224:225]
	v_pk_add_f32 v[22:23], v[22:23], v[226:227]
	v_pk_add_f32 v[16:17], v[16:17], v[228:229]
	v_pk_add_f32 v[18:19], v[18:19], v[230:231]
	s_mov_b64 exec, s[98:99]
	ds_write_b128 v234, v[20:23]
	ds_write_b128 v235, v[16:19]
	s_mov_b64 exec, -1
	ds_read_b128 v[238:241], v236
	s_mov_b64 exec, s[100:101]
	ds_write_b128 v234, v[20:23]
	ds_write_b128 v235, v[16:19]
	s_mov_b64 exec, -1
	ds_read_b128 v[242:245], v236
	s_waitcnt lgkmcnt(3)
	global_store_dwordx4 v233, v[238:241], s[50:51] offset:512 nt
	s_waitcnt lgkmcnt(0)
	global_store_dwordx4 v237, v[242:245], s[50:51] offset:512 nt
	v_add_u32_e32 v233, 0x10000, v233
	v_add_u32_e32 v237, 0x10000, v237
	s_waitcnt vmcnt(28)
	v_lshlrev_b32_e32 v224, 16, v212
	v_and_b32_e32 v225, 0xffff0000, v212
	v_lshlrev_b32_e32 v226, 16, v213
	v_and_b32_e32 v227, 0xffff0000, v213
	v_lshlrev_b32_e32 v228, 16, v214
	v_and_b32_e32 v229, 0xffff0000, v214
	v_lshlrev_b32_e32 v230, 16, v215
	v_and_b32_e32 v231, 0xffff0000, v215
	v_pk_add_f32 v[12:13], v[12:13], v[224:225]
	v_pk_add_f32 v[14:15], v[14:15], v[226:227]
	v_pk_add_f32 v[8:9], v[8:9], v[228:229]
	v_pk_add_f32 v[10:11], v[10:11], v[230:231]
	s_mov_b64 exec, s[98:99]
	ds_write_b128 v234, v[12:15]
	ds_write_b128 v235, v[8:11]
	s_mov_b64 exec, -1
	ds_read_b128 v[238:241], v236
	s_mov_b64 exec, s[100:101]
	ds_write_b128 v234, v[12:15]
	ds_write_b128 v235, v[8:11]
	s_mov_b64 exec, -1
	ds_read_b128 v[242:245], v236
	s_waitcnt lgkmcnt(3)
	global_store_dwordx4 v233, v[238:241], s[50:51] nt
	s_waitcnt lgkmcnt(0)
	global_store_dwordx4 v237, v[242:245], s[50:51] nt
	v_lshlrev_b32_e32 v224, 16, v216
	v_and_b32_e32 v225, 0xffff0000, v216
	v_lshlrev_b32_e32 v226, 16, v217
	v_and_b32_e32 v227, 0xffff0000, v217
	v_lshlrev_b32_e32 v228, 16, v218
	v_and_b32_e32 v229, 0xffff0000, v218
	v_lshlrev_b32_e32 v230, 16, v219
	v_and_b32_e32 v231, 0xffff0000, v219
	v_pk_add_f32 v[4:5], v[4:5], v[224:225]
	v_pk_add_f32 v[6:7], v[6:7], v[226:227]
	v_pk_add_f32 v[0:1], v[0:1], v[228:229]
	v_pk_add_f32 v[2:3], v[2:3], v[230:231]
	s_mov_b64 exec, s[98:99]
	ds_write_b128 v234, v[4:7]
	ds_write_b128 v235, v[0:3]
	s_mov_b64 exec, -1
	ds_read_b128 v[238:241], v236
	s_mov_b64 exec, s[100:101]
	ds_write_b128 v234, v[4:7]
	ds_write_b128 v235, v[0:3]
	s_mov_b64 exec, -1
	ds_read_b128 v[242:245], v236
	s_waitcnt lgkmcnt(3)
	global_store_dwordx4 v233, v[238:241], s[50:51] offset:512 nt
	s_waitcnt lgkmcnt(0)
	global_store_dwordx4 v237, v[242:245], s[50:51] offset:512 nt
	s_andn2_b64 vcc, exec, s[0:1]
	s_mov_b64 s[0:1], -1
	s_cbranch_vccnz .LBB0_805
	s_andn2_b64 vcc, exec, s[4:5]
	s_cbranch_vccnz .LBB0_804
	s_barrier
	s_branch .LBB0_804
